# MLA loop VALU trims: PV LDS addresses via offset immediates, DMA M0 values formed on scalar unit
# speedup vs baseline: 1.0633x; 1.0063x over previous
.LBB0_562:
	s_waitcnt vmcnt(7)
	s_add_i32 s7, s6, -3
	s_cmpk_gt_u32 s7, 0x84
	s_barrier
	s_cbranch_scc1 .LBB0_564
	s_and_b32 s7, s6, 0xff
	s_mulk_i32 s7, 0xab
	s_lshr_b32 s7, s7, 9
	s_mul_i32 s7, s7, 3
	s_sub_i32 s7, s6, s7
	s_and_b32 s7, s7, 0xff
	s_mulk_i32 s7, 0x3000
	v_readfirstlane_b32 s100, v167
	s_and_b32 s101, s5, 0x6000
	s_add_i32 s7, s7, s100
	s_add_i32 s101, s101, s100
	s_add_i32 m0, s7, 0x0
	v_lshl_add_u64 v[64:65], v[150:151], 0, s[20:21]
	global_load_lds_dwordx4 v[156:157], off
	s_add_i32 m0, s7, 0x1000
	s_nop 0
	global_load_lds_dwordx4 v[154:155], off
	s_add_i32 m0, s7, 0x2000
	s_nop 0
	global_load_lds_dwordx4 v[152:153], off
	s_add_i32 m0, s101, 0x9000
	s_nop 0
	global_load_lds_dwordx4 v[150:151], off
	s_add_i32 m0, s101, 0xa000
	s_nop 0
	global_load_lds_dwordx4 v[64:65], off

.LBB0_566:
	v_sub_f32_e32 v80, v80, v165
	v_exp_f32_e32 v176, v80
	v_sub_f32_e32 v81, v81, v165
	v_exp_f32_e32 v177, v81
	v_sub_f32_e32 v81, v82, v165
	v_exp_f32_e32 v199, v81
	v_sub_f32_e32 v81, v83, v165
	v_exp_f32_e32 v200, v81
	v_sub_f32_e32 v81, v84, v165
	v_add_f32_e32 v80, 0, v176
	v_exp_f32_e32 v201, v81
	v_sub_f32_e32 v81, v85, v165
	v_add_f32_e32 v80, v177, v80
	v_exp_f32_e32 v202, v81
	v_sub_f32_e32 v81, v86, v165
	v_add_f32_e32 v80, v199, v80
	v_exp_f32_e32 v203, v81
	v_sub_f32_e32 v81, v87, v165
	v_add_f32_e32 v80, v200, v80
	v_exp_f32_e32 v204, v81
	v_sub_f32_e32 v81, v88, v165
	v_add_f32_e32 v80, v201, v80
	v_exp_f32_e32 v205, v81
	v_sub_f32_e32 v81, v89, v165
	v_add_f32_e32 v80, v202, v80
	v_exp_f32_e32 v206, v81
	v_sub_f32_e32 v81, v90, v165
	v_add_f32_e32 v80, v203, v80
	v_exp_f32_e32 v207, v81
	v_sub_f32_e32 v81, v91, v165
	v_add_f32_e32 v80, v204, v80
	v_exp_f32_e32 v208, v81
	v_sub_f32_e32 v81, v92, v165
	v_add_f32_e32 v80, v205, v80
	v_exp_f32_e32 v209, v81
	v_sub_f32_e32 v81, v93, v165
	v_add_f32_e32 v80, v206, v80
	v_exp_f32_e32 v210, v81
	v_sub_f32_e32 v81, v94, v165
	v_add_f32_e32 v80, v207, v80
	v_exp_f32_e32 v211, v81
	v_sub_f32_e32 v81, v95, v165
	v_add_f32_e32 v80, v208, v80
	v_exp_f32_e32 v212, v81
	s_add_i32 s7, s5, 0xffffa000
	v_add_f32_e32 v80, v209, v80
	s_and_b32 s7, s7, 0x6000
	v_add_f32_e32 v80, v210, v80
	s_add_i32 s7, s7, 16
	v_add_f32_e32 v80, v211, v80
	s_add_i32 s8, s7, 0x800
	s_add_i32 s9, s7, 0x1000
	s_add_i32 s10, s7, 0x1800
	v_add_f32_e32 v213, v212, v80
	v_add_u32_e32 v252, s7, v162
	v_add_u32_e32 v253, s7, v163
	ds_read_b64 v[80:81], v252
	ds_read_b64 v[82:83], v253
	ds_read_b64 v[84:85], v252 offset:2048
	ds_read_b64 v[86:87], v253 offset:2048
	ds_read_b64 v[88:89], v252 offset:4096
	ds_read_b64 v[90:91], v253 offset:4096
	ds_read_b64 v[92:93], v252 offset:6144
	ds_read_b64 v[94:95], v253 offset:6144
	v_cvt_pk_bf16_f32 v198, v176, v177
	v_cvt_pk_bf16_f32 v199, v199, v200
	v_cvt_pk_bf16_f32 v200, v201, v202
	v_cvt_pk_bf16_f32 v201, v203, v204
	s_add_i32 s6, s6, 1
	s_waitcnt lgkmcnt(0)
	s_addk_i32 s5, 0x2000
	v_mfma_f32_32x32x16_bf16 v[48:63], v[80:83], v[198:201], v[48:63]
	v_add_u32_e32 v254, s7, v161
	v_add_u32_e32 v255, s7, v160
	ds_read_b64 v[80:81], v254
	ds_read_b64 v[82:83], v255
	s_addk_i32 s36, 0x3000
	s_add_i32 s4, s4, 1
	v_add_f32_e32 v164, v164, v213
	v_mfma_f32_32x32x16_bf16 v[32:47], v[84:87], v[198:201], v[32:47]
	ds_read_b64 v[84:85], v254 offset:2048
	ds_read_b64 v[86:87], v255 offset:2048
	v_lshl_add_u64 v[150:151], v[150:151], 0, 64
	v_lshl_add_u64 v[152:153], v[152:153], 0, v[148:149]
	v_lshl_add_u64 v[154:155], v[154:155], 0, v[146:147]
	v_mfma_f32_32x32x16_bf16 v[16:31], v[88:91], v[198:201], v[16:31]
	ds_read_b64 v[88:89], v254 offset:4096
	ds_read_b64 v[90:91], v255 offset:4096
	v_lshl_add_u64 v[156:157], v[156:157], 0, v[96:97]
	s_cmp_eq_u32 s36, 0x192000
	v_mfma_f32_32x32x16_bf16 v[0:15], v[92:95], v[198:201], v[0:15]
	ds_read_b64 v[92:93], v254 offset:6144
	ds_read_b64 v[94:95], v255 offset:6144
	v_cvt_pk_bf16_f32 v198, v205, v206
	v_cvt_pk_bf16_f32 v199, v207, v208
	v_cvt_pk_bf16_f32 v200, v209, v210
	v_cvt_pk_bf16_f32 v201, v211, v212
	s_nop 0
	s_waitcnt lgkmcnt(0)
	s_nop 0
	v_mfma_f32_32x32x16_bf16 v[48:63], v[80:83], v[198:201], v[48:63]
	v_mfma_f32_32x32x16_bf16 v[32:47], v[84:87], v[198:201], v[32:47]
	v_mfma_f32_32x32x16_bf16 v[16:31], v[88:91], v[198:201], v[16:31]
	v_mfma_f32_32x32x16_bf16 v[0:15], v[92:95], v[198:201], v[0:15]
	s_cbranch_scc1 .LBB0_766
	v_mov_b64_e32 v[94:95], v[78:79]
	v_mov_b64_e32 v[92:93], v[76:77]
	v_mov_b64_e32 v[90:91], v[74:75]
	v_mov_b64_e32 v[88:89], v[72:73]
	v_mov_b64_e32 v[86:87], v[70:71]
	v_mov_b64_e32 v[84:85], v[68:69]
	v_mov_b64_e32 v[82:83], v[66:67]
	v_mov_b64_e32 v[80:81], v[64:65]
	s_branch .LBB0_562

.LBB0_582:
	s_waitcnt vmcnt(7)
	s_add_i32 s8, s7, 3
	s_cmp_ge_u32 s8, s4
	s_barrier
	s_cbranch_scc1 .LBB0_584
	s_mul_hi_u32 s8, s0, 0xaaaaaaab
	s_lshr_b32 s8, s8, 1
	s_mul_i32 s8, s8, 0x9000
	s_sub_i32 s8, s1, s8
	v_readfirstlane_b32 s100, v200
	s_add_i32 s101, s36, 0x6000
	s_and_b32 s101, s101, 0x6000
	s_add_i32 s8, s8, s100
	s_add_i32 s101, s101, s100
	s_add_i32 m0, s8, 0x9000
	v_lshl_add_u64 v[64:65], v[166:167], 0, s[20:21]
	global_load_lds_dwordx4 v[172:173], off
	s_add_i32 m0, s8, 0xa000
	s_nop 0
	global_load_lds_dwordx4 v[170:171], off
	s_add_i32 m0, s8, 0xb000
	s_nop 0
	global_load_lds_dwordx4 v[168:169], off
	s_add_i32 m0, s101, 0x9000
	s_nop 0
	global_load_lds_dwordx4 v[166:167], off
	s_add_i32 m0, s101, 0xa000
	s_nop 0
	global_load_lds_dwordx4 v[64:65], off

.LBB0_586:
	v_sub_f32_e32 v80, v80, v198
	v_exp_f32_e32 v209, v80
	v_sub_f32_e32 v81, v81, v198
	v_exp_f32_e32 v210, v81
	v_sub_f32_e32 v81, v82, v198
	v_exp_f32_e32 v211, v81
	v_sub_f32_e32 v81, v83, v198
	v_exp_f32_e32 v212, v81
	v_sub_f32_e32 v81, v84, v198
	v_add_f32_e32 v80, 0, v209
	v_exp_f32_e32 v213, v81
	v_sub_f32_e32 v81, v85, v198
	v_add_f32_e32 v80, v210, v80
	v_exp_f32_e32 v214, v81
	v_sub_f32_e32 v81, v86, v198
	v_add_f32_e32 v80, v211, v80
	v_exp_f32_e32 v215, v81
	v_sub_f32_e32 v81, v87, v198
	v_add_f32_e32 v80, v212, v80
	v_exp_f32_e32 v216, v81
	v_sub_f32_e32 v81, v88, v198
	v_add_f32_e32 v80, v213, v80
	v_exp_f32_e32 v217, v81
	v_sub_f32_e32 v81, v89, v198
	v_add_f32_e32 v80, v214, v80
	v_exp_f32_e32 v218, v81
	v_sub_f32_e32 v81, v90, v198
	v_add_f32_e32 v80, v215, v80
	v_exp_f32_e32 v219, v81
	v_sub_f32_e32 v81, v91, v198
	v_add_f32_e32 v80, v216, v80
	v_exp_f32_e32 v220, v81
	v_sub_f32_e32 v81, v92, v198
	v_add_f32_e32 v80, v217, v80
	v_exp_f32_e32 v221, v81
	v_sub_f32_e32 v81, v93, v198
	v_add_f32_e32 v80, v218, v80
	v_exp_f32_e32 v222, v81
	v_sub_f32_e32 v81, v94, v198
	v_add_f32_e32 v80, v219, v80
	v_exp_f32_e32 v223, v81
	v_sub_f32_e32 v81, v95, v198
	v_add_f32_e32 v80, v220, v80
	v_exp_f32_e32 v224, v81
	v_add_f32_e32 v80, v221, v80
	s_and_b32 s8, s36, 0x6000
	v_add_f32_e32 v80, v222, v80
	s_add_i32 s8, s8, 16
	v_add_f32_e32 v80, v223, v80
	s_add_i32 s9, s8, 0x800
	s_add_i32 s10, s8, 0x1000
	s_add_i32 s11, s8, 0x1800
	v_add_f32_e32 v225, v224, v80
	v_add_u32_e32 v252, s8, v157
	v_add_u32_e32 v253, s8, v176
	ds_read_b64 v[80:81], v252
	ds_read_b64 v[82:83], v253
	ds_read_b64 v[84:85], v252 offset:2048
	ds_read_b64 v[86:87], v253 offset:2048
	ds_read_b64 v[88:89], v252 offset:4096
	ds_read_b64 v[90:91], v253 offset:4096
	ds_read_b64 v[92:93], v252 offset:6144
	ds_read_b64 v[94:95], v253 offset:6144
	v_cvt_pk_bf16_f32 v210, v209, v210
	v_cvt_pk_bf16_f32 v211, v211, v212
	v_cvt_pk_bf16_f32 v212, v213, v214
	v_cvt_pk_bf16_f32 v213, v215, v216
	s_addk_i32 s1, 0x3000
	s_waitcnt lgkmcnt(0)
	s_addk_i32 s36, 0x2000
	v_mfma_f32_32x32x16_bf16 v[48:63], v[80:83], v[210:213], v[48:63]
	v_add_u32_e32 v254, s8, v149
	v_add_u32_e32 v255, s8, v153
	ds_read_b64 v[80:81], v254
	ds_read_b64 v[82:83], v255
	s_add_i32 s6, s6, 1
	s_add_i32 s0, s0, 1
	s_add_i32 s7, s7, 1
	v_mfma_f32_32x32x16_bf16 v[32:47], v[84:87], v[210:213], v[32:47]
	ds_read_b64 v[84:85], v254 offset:2048
	ds_read_b64 v[86:87], v255 offset:2048
	v_add_f32_e32 v177, v177, v225
	v_lshl_add_u64 v[166:167], v[166:167], 0, 64
	v_lshl_add_u64 v[168:169], v[168:169], 0, v[164:165]
	v_mfma_f32_32x32x16_bf16 v[16:31], v[88:91], v[210:213], v[16:31]
	ds_read_b64 v[88:89], v254 offset:4096
	ds_read_b64 v[90:91], v255 offset:4096
	v_lshl_add_u64 v[170:171], v[170:171], 0, v[162:163]
	v_lshl_add_u64 v[172:173], v[172:173], 0, v[96:97]
	s_cmp_eq_u32 s5, s1
	v_mfma_f32_32x32x16_bf16 v[0:15], v[92:95], v[210:213], v[0:15]
	ds_read_b64 v[92:93], v254 offset:6144
	ds_read_b64 v[94:95], v255 offset:6144
	v_cvt_pk_bf16_f32 v210, v217, v218
	v_cvt_pk_bf16_f32 v211, v219, v220
	v_cvt_pk_bf16_f32 v212, v221, v222
	v_cvt_pk_bf16_f32 v213, v223, v224
	s_nop 0
	s_waitcnt lgkmcnt(0)
	s_nop 0
	v_mfma_f32_32x32x16_bf16 v[48:63], v[80:83], v[210:213], v[48:63]
	v_mfma_f32_32x32x16_bf16 v[32:47], v[84:87], v[210:213], v[32:47]
	v_mfma_f32_32x32x16_bf16 v[16:31], v[88:91], v[210:213], v[16:31]
	v_mfma_f32_32x32x16_bf16 v[0:15], v[92:95], v[210:213], v[0:15]
	s_cbranch_scc1 .LBB0_588
	v_mov_b64_e32 v[94:95], v[78:79]
	v_mov_b64_e32 v[92:93], v[76:77]
	v_mov_b64_e32 v[90:91], v[74:75]
	v_mov_b64_e32 v[88:89], v[72:73]
	v_mov_b64_e32 v[86:87], v[70:71]
	v_mov_b64_e32 v[84:85], v[68:69]
	v_mov_b64_e32 v[82:83], v[66:67]
	v_mov_b64_e32 v[80:81], v[64:65]
	s_branch .LBB0_582

.LBB0_609:
	s_waitcnt vmcnt(7)
	s_add_i32 s6, s5, 3
	v_readlane_b32 s7, v227, 15
	s_cmp_ge_u32 s6, s7
	s_barrier
	s_cbranch_scc1 .LBB0_611
	s_mul_hi_u32 s6, s1, 0xaaaaaaab
	s_lshr_b32 s6, s6, 1
	s_mul_i32 s6, s6, 0x9000
	s_sub_i32 s6, s4, s6
	v_readfirstlane_b32 s100, v202
	s_add_i32 s101, s36, 0x6000
	s_and_b32 s101, s101, 0x6000
	s_add_i32 s6, s6, s100
	s_add_i32 s101, s101, s100
	s_add_i32 m0, s6, 0x9000
	v_lshl_add_u64 v[64:65], v[166:167], 0, s[20:21]
	global_load_lds_dwordx4 v[172:173], off
	s_add_i32 m0, s6, 0xa000
	s_nop 0
	global_load_lds_dwordx4 v[170:171], off
	s_add_i32 m0, s6, 0xb000
	s_nop 0
	global_load_lds_dwordx4 v[168:169], off
	s_add_i32 m0, s101, 0x9000
	s_nop 0
	global_load_lds_dwordx4 v[166:167], off
	s_add_i32 m0, s101, 0xa000
	s_nop 0
	global_load_lds_dwordx4 v[64:65], off

.LBB0_613:
	v_sub_f32_e32 v80, v80, v198
	v_exp_f32_e32 v210, v80
	v_sub_f32_e32 v81, v81, v198
	v_exp_f32_e32 v211, v81
	v_sub_f32_e32 v81, v82, v198
	v_exp_f32_e32 v212, v81
	v_sub_f32_e32 v81, v83, v198
	v_exp_f32_e32 v213, v81
	v_sub_f32_e32 v81, v84, v198
	v_add_f32_e32 v80, 0, v210
	v_exp_f32_e32 v214, v81
	v_sub_f32_e32 v81, v85, v198
	v_add_f32_e32 v80, v211, v80
	v_exp_f32_e32 v215, v81
	v_sub_f32_e32 v81, v86, v198
	v_add_f32_e32 v80, v212, v80
	v_exp_f32_e32 v216, v81
	v_sub_f32_e32 v81, v87, v198
	v_add_f32_e32 v80, v213, v80
	v_exp_f32_e32 v217, v81
	v_sub_f32_e32 v81, v88, v198
	v_add_f32_e32 v80, v214, v80
	v_exp_f32_e32 v218, v81
	v_sub_f32_e32 v81, v89, v198
	v_add_f32_e32 v80, v215, v80
	v_exp_f32_e32 v219, v81
	v_sub_f32_e32 v81, v90, v198
	v_add_f32_e32 v80, v216, v80
	v_exp_f32_e32 v220, v81
	v_sub_f32_e32 v81, v91, v198
	v_add_f32_e32 v80, v217, v80
	v_exp_f32_e32 v221, v81
	v_sub_f32_e32 v81, v92, v198
	v_add_f32_e32 v80, v218, v80
	v_exp_f32_e32 v222, v81
	v_sub_f32_e32 v81, v93, v198
	v_add_f32_e32 v80, v219, v80
	v_exp_f32_e32 v223, v81
	v_sub_f32_e32 v81, v94, v198
	v_add_f32_e32 v80, v220, v80
	v_exp_f32_e32 v224, v81
	v_sub_f32_e32 v81, v95, v198
	v_add_f32_e32 v80, v221, v80
	v_exp_f32_e32 v225, v81
	v_add_f32_e32 v80, v222, v80
	s_and_b32 s6, s36, 0x6000
	v_add_f32_e32 v80, v223, v80
	s_add_i32 s6, s6, 16
	v_add_f32_e32 v80, v224, v80
	s_add_i32 s7, s6, 0x800
	s_add_i32 s8, s6, 0x1000
	s_add_i32 s9, s6, 0x1800
	v_add_f32_e32 v226, v225, v80
	v_add_u32_e32 v252, s6, v157
	v_add_u32_e32 v253, s6, v176
	ds_read_b64 v[80:81], v252
	ds_read_b64 v[82:83], v253
	ds_read_b64 v[84:85], v252 offset:2048
	ds_read_b64 v[86:87], v253 offset:2048
	ds_read_b64 v[88:89], v252 offset:4096
	ds_read_b64 v[90:91], v253 offset:4096
	ds_read_b64 v[92:93], v252 offset:6144
	ds_read_b64 v[94:95], v253 offset:6144
	v_cvt_pk_bf16_f32 v210, v210, v211
	v_cvt_pk_bf16_f32 v211, v212, v213
	v_cvt_pk_bf16_f32 v212, v214, v215
	v_cvt_pk_bf16_f32 v213, v216, v217
	s_addk_i32 s4, 0x3000
	s_waitcnt lgkmcnt(0)
	s_addk_i32 s36, 0x2000
	v_mfma_f32_32x32x16_bf16 v[48:63], v[80:83], v[210:213], v[48:63]
	v_add_u32_e32 v254, s6, v153
	v_add_u32_e32 v255, s6, v149
	ds_read_b64 v[80:81], v254
	ds_read_b64 v[82:83], v255
	s_add_i32 s0, s0, 1
	s_add_i32 s1, s1, 1
	s_add_i32 s5, s5, 1
	v_mfma_f32_32x32x16_bf16 v[32:47], v[84:87], v[210:213], v[32:47]
	ds_read_b64 v[84:85], v254 offset:2048
	ds_read_b64 v[86:87], v255 offset:2048
	v_readlane_b32 s6, v227, 16
	v_add_f32_e32 v177, v177, v226
	v_lshl_add_u64 v[166:167], v[166:167], 0, 64
	v_mfma_f32_32x32x16_bf16 v[16:31], v[88:91], v[210:213], v[16:31]
	ds_read_b64 v[88:89], v254 offset:4096
	ds_read_b64 v[90:91], v255 offset:4096
	v_lshl_add_u64 v[168:169], v[168:169], 0, v[164:165]
	v_lshl_add_u64 v[170:171], v[170:171], 0, v[162:163]
	v_lshl_add_u64 v[172:173], v[172:173], 0, v[96:97]
	v_mfma_f32_32x32x16_bf16 v[0:15], v[92:95], v[210:213], v[0:15]
	ds_read_b64 v[92:93], v254 offset:6144
	ds_read_b64 v[94:95], v255 offset:6144
	v_cvt_pk_bf16_f32 v210, v218, v219
	v_cvt_pk_bf16_f32 v211, v220, v221
	v_cvt_pk_bf16_f32 v212, v222, v223
	v_cvt_pk_bf16_f32 v213, v224, v225
	s_cmp_eq_u32 s6, s4
	s_waitcnt lgkmcnt(0)
	s_nop 0
	v_mfma_f32_32x32x16_bf16 v[48:63], v[80:83], v[210:213], v[48:63]
	v_mfma_f32_32x32x16_bf16 v[32:47], v[84:87], v[210:213], v[32:47]
	v_mfma_f32_32x32x16_bf16 v[16:31], v[88:91], v[210:213], v[16:31]
	v_mfma_f32_32x32x16_bf16 v[0:15], v[92:95], v[210:213], v[0:15]
	s_cbranch_scc1 .LBB0_615
	v_mov_b64_e32 v[94:95], v[78:79]
	v_mov_b64_e32 v[92:93], v[76:77]
	v_mov_b64_e32 v[90:91], v[74:75]
	v_mov_b64_e32 v[88:89], v[72:73]
	v_mov_b64_e32 v[86:87], v[70:71]
	v_mov_b64_e32 v[84:85], v[68:69]
	v_mov_b64_e32 v[82:83], v[66:67]
	v_mov_b64_e32 v[80:81], v[64:65]
	s_branch .LBB0_609
